# v50 + attention phase: every workgroup takes its retention-scan and sample-stream items before its prompt attention items (same items and code, different order)
# baseline (speedup 1.0000x reference)
; #define LAS __attribute__((address_space(3)))
; __global__ void __launch_bounds__(512, 2) hse_fwd(Params P) {
;     ...
;             { const int n_mla = GNB * 8 * 16, n_band = GNB * 8 * 32, n_scan = GNB * 8 * 16, n_smp = gr.samp ? SB * 8 : 0;
;               const int n_items = n_mla + n_band + n_scan + 2 * n_smp;
;               const int bx = ((G & 7) == 0 && n_mla % G == 0 && n_band % G == 0) ? (bid & 7) * (G >> 3) + (bid >> 3) : bid;
;               const int l31 = lane & 31;
;               for (int it = bid; it < n_items; it += G) {
;                 if (it < n_mla) {
;                     const int itx = it - bid + bx;
;                     const int x = itx & 15, h = (itx >> 4) & 7, bl = itx >> 7;
;                     MlaLoader L; L.tid = tid; L.kn = (const char*)(knope + (size_t)(bl * TT) * 1024 + h * 128); L.kr = (const char*)(kropa + (size_t)(bl * TT) * 64); L.vt = (const char*)(vtb + (size_t)(h * 128) * VT_LD + bl * TT); L.nkeys = TT;
; #pragma unroll 1
;                     for (int pass = 0; pass < 2; ++pass) { const int qb = (pass & 1) == 0 ? x : 31 - x; const int rr = bl * TT + qb * 256 + wave * 32 + l31; const int cw = 4 * qb + (wave >> 1);
;                         attn_unit<192, false, MlaLoader>(tid, lds, L, qbuf + (size_t)rr * 1536 + h * 192, true, 0, 4 * qb + 4, 0, cw + 1, TT, 0, 0, ocat + (size_t)rr * 3072 + h * 128); }
;                 } else if (it < n_mla + n_band) {
;                     const int u = it - n_mla - bid + bx, qb = u & 31, h = (u >> 5) & 7, bl = u >> 8;
;                     __syncthreads();
;                     { LAS float* bt = (LAS float*)(lds + AT_BIAS); if (tid < 257) bt[tid] = INP(17)[((size_t)l * 8 + h) * 257 + tid] * LOG2E; }
;                     BandLoader L; L.tid = tid; L.kc = nullptr; L.vc = nullptr; L.ncache = 0; L.kp = (const char*)(proj + (size_t)(bl * TT) * NPROJ + PC_KB + h * 128); L.vp = (const char*)(proj + (size_t)(bl * TT) * NPROJ + PC_VB + h * 128); L.nkeys = TT;
;                     const int rr = bl * TT + qb * 256 + wave * 32 + l31; const int cw = 4 * qb + (wave >> 1); const int t0 = (4 * qb - 8) > 0 ? (4 * qb - 8) : 0, wt0 = (cw - 8) > 0 ? (cw - 8) : 0;
;                     attn_unit<128, true, BandLoader>(tid, lds, L, proj + (size_t)rr * NPROJ + PC_QB + h * 128, true, t0, 4 * qb + 4, wt0, cw + 1, TT, qb * 256 + wave * 32 + l31, 0, ocat + (size_t)rr * 3072 + 1024 + h * 128);
.LBB0_4804:
	s_andn2_b64 vcc, exec, s[0:1]
	s_cbranch_vccnz .LBB0_5078
	v_readlane_b32 s1, v255, 5
	s_waitcnt vmcnt(0)
	s_barrier
	s_mov_b32 s101, 0
	v_mov_b32_e32 v1, s1
	v_mbcnt_lo_u32_b32 v0, -1, 0
	v_mbcnt_hi_u32_b32 v0, -1, v0
	ds_read_b128 v[2:5], v1
	v_readlane_b32 s0, v253, 8
	v_readlane_b32 s8, v254, 5
	v_readlane_b32 s9, v254, 6
	v_or_b32_e32 v184, s0, v0
	s_waitcnt lgkmcnt(0)
	v_readfirstlane_b32 s5, v5
	v_readfirstlane_b32 s0, v184
	v_readfirstlane_b32 s4, v4
	v_readfirstlane_b32 s7, v3
	v_readfirstlane_b32 s6, v2
	s_andn2_b64 vcc, exec, s[8:9]
	s_mov_b32 s28, s46
	s_cbranch_vccnz .LBB0_4808
	v_readlane_b32 s8, v254, 44
	v_readlane_b32 s9, v254, 45
	s_andn2_b64 vcc, exec, s[8:9]
	s_mov_b32 s28, s46
	s_cbranch_vccnz .LBB0_4808
	v_readlane_b32 s28, v254, 46
.LBB0_4808:
	v_readlane_b32 s1, v255, 44
	s_lshl_b32 s29, s1, 9
	s_bitset1_b32 s29, 10
	s_cmp_ge_i32 s46, s29
	s_cbranch_scc1 .LBB0_5027
	v_readlane_b32 s1, v255, 44
	s_lshl_b32 s34, s1, 8
	s_movk_i32 s8, 0x101
	s_lshl_b32 s1, s1, 1
	s_or_b32 s35, s34, 0x400
	v_cmp_gt_i32_e64 s[36:37], s8, v184
	v_readlane_b32 s8, v253, 19
	v_and_b32_e32 v1, 31, v0
	v_cmp_gt_u32_e32 vcc, 16, v1
	v_lshl_add_u32 v189, v184, 2, s8
	s_add_u32 s8, s4, 0x19610800
	s_addc_u32 s9, s5, 0
	s_cmp_lt_u32 s0, 64
	s_cselect_b64 s[10:11], -1, 0
	s_and_b64 s[12:13], s[10:11], vcc
	s_add_u32 s66, s4, 0x392e2800
	s_addc_u32 s67, s5, 0
	s_add_u32 s68, s4, 0x38cd0800
	s_addc_u32 s69, s5, 0
	s_add_u32 s70, s4, 0x3f402800
	s_addc_u32 s71, s5, 0
	s_add_u32 s42, s4, 0x34310800
	s_addc_u32 s43, s5, 0
	v_bfe_u32 v3, v0, 5, 1
	s_movk_i32 s14, 0x110
	s_add_u32 s44, s4, 0x45522800
	v_cndmask_b32_e32 v191, 15, v1, vcc
	v_mad_u32_u24 v4, v1, s14, 0
	v_lshlrev_b32_e32 v2, 4, v3
	s_movk_i32 s14, 0xff78
	v_readlane_b32 s16, v253, 29
	s_addc_u32 s45, s5, 0
	v_lshlrev_b32_e32 v186, 3, v3
	v_add_u32_e32 v208, v4, v2
	v_mul_u32_u24_e32 v5, 0x88, v1
	v_mad_i32_i24 v4, v1, s14, v4
	v_lshlrev_b32_e32 v188, 2, v3
	v_subrev_u32_e32 v3, s16, v191
	v_mul_u32_u24_e32 v1, 0x108, v1
	s_add_u32 s72, s4, 0x4b822800
	v_readlane_b32 s14, v255, 41
	v_add_u32_e32 v211, 0x8000, v3
	v_add3_u32 v212, v4, v1, v2
	s_addc_u32 s73, s5, 0
	s_or_b32 s74, s1, s14
	v_lshlrev_b32_e32 v1, 5, v0
	v_bfe_u32 v3, v0, 1, 5
	s_ashr_i32 s1, s0, 1
	v_and_or_b32 v190, v1, 32, v3
	v_readlane_b32 s14, v253, 4
	v_mov_b32_e32 v1, s1
	s_movk_i32 s1, 0xffe0
	v_add_u32_e32 v209, v4, v186
	v_and_b32_e32 v4, 1, v0
	s_sub_i32 s75, s28, s14
	v_bfi_b32 v213, s1, v1, v0
	s_ashr_i32 s76, s0, 7
	v_mov_b64_e32 v[0:1], s[4:5]
	s_movk_i32 s0, 0x3ffe
	s_addk_i32 s75, 0xff00
	v_mad_u64_u32 v[0:1], s[0:1], v4, s0, v[0:1]
	v_mov_b32_e32 v187, v32
	v_mov_b32_e32 v3, v32
	s_cmp_gt_i32 s76, 2
	s_mov_b64 s[0:1], 0x4d89a800
	v_ashrrev_i32_e32 v185, 31, v184
	v_or_b32_e32 v207, 0x400, v191
	v_add_u32_e32 v210, 0xc800, v209
	v_cmp_eq_u32_e64 s[38:39], 0, v4
	v_cmp_eq_u32_e64 s[40:41], 1, v4
	v_lshl_add_u64 v[192:193], s[42:43], 0, v[2:3]
	v_add3_u32 v214, 0, v186, v5
	v_lshl_add_u64 v[194:195], s[44:45], 0, v[186:187]
	s_cselect_b64 s[46:47], -1, 0
	s_sub_i32 s77, 0x8000, s16
	v_lshl_add_u64 v[200:201], v[0:1], 0, s[0:1]
	s_lshl_b32 s78, s28, 6
	s_mov_b32 s79, s28
	s_mov_b32 s80, s28
	v_readlane_b32 s81, v254, 18
	v_readlane_b32 s82, v254, 61
	v_readlane_b32 s83, v254, 60
	s_mov_b32 s84, s14
	s_mov_b32 s85, s14
	v_readlane_b32 s15, v253, 5
	s_mov_b32 s101, 1
	v_readlane_b32 s0, v253, 0
	s_mul_i32 s0, s0, 3
	s_add_i32 s85, s85, s0
	s_add_i32 s84, s84, s0
	s_add_i32 s83, s83, s0
	s_add_i32 s82, s82, s0
	s_add_i32 s80, s80, s0
	s_add_i32 s79, s79, s0
	v_readlane_b32 s0, v254, 19
	s_mul_i32 s0, s0, 3
	s_add_i32 s81, s81, s0
	v_readlane_b32 s0, v253, 21
	s_mul_i32 s0, s0, 3
	s_add_i32 s78, s78, s0
	s_branch .LBB0_4811

; __global__ void __launch_bounds__(512, 2) hse_fwd(Params P) {
;     ...
;               for (int it = bid; it < n_items; it += G) {
.LBB0_5027:
	s_cmp_lg_u32 s101, 1
	s_cbranch_scc1 .Lm4_done
	s_mov_b32 s101, 2
	v_readlane_b32 s85, v253, 4
	v_readlane_b32 s83, v254, 60
	v_readlane_b32 s82, v254, 61
	v_readlane_b32 s81, v254, 18
	s_mov_b32 s84, s85
	s_mov_b32 s80, s28
	s_mov_b32 s79, s28
	s_lshl_b32 s78, s28, 6
	v_readlane_b32 s29, v253, 0
	s_mul_i32 s29, s29, 3
	s_branch .LBB0_4811
